# KV GEMM: per-row sum-of-squares words loaded at unit start into free VGPRs (epilogue no longer waits behind the next unit's staging loads); first two counted waits of the peeled iteration relaxed for
# speedup vs baseline: 1.0033x; 1.0003x over previous
.LBB0_838:
	s_ashr_i32 s29, s28, 31
	s_lshl_b64 s[10:11], s[28:29], 20
	s_add_u32 s30, s37, s10
	s_addc_u32 s31, s39, s11
	s_and_b64 s[10:11], s[4:5], exec
	s_cselect_b32 s12, s31, s7
	s_cselect_b32 s13, s30, s6
	s_ashr_i32 s27, s26, 31
	s_lshl_b64 s[10:11], s[26:27], 20
	s_add_u32 s34, s14, s10
	s_addc_u32 s35, s36, s11
	s_and_b64 s[10:11], s[4:5], exec
	s_cselect_b32 s27, s35, s9
	s_cselect_b32 s29, s34, s8
	s_add_u32 s6, s6, 0x80080
	s_addc_u32 s7, s7, 0
	s_add_u32 s42, s8, 0x100
	s_addc_u32 s43, s9, 0
	s_mov_b32 s44, -2
	v_and_b32_e32 v250, 63, v0
	v_lshlrev_b32_e32 v250, 2, v250
	s_lshl_b32 s98, s58, 8
	s_add_i32 s98, s98, s57
	s_lshl_b32 s98, s98, 2
	s_add_u32 s98, s24, s98
	s_addc_u32 s99, s25, 0
	s_lshr_b32 m0, s53, 2
	s_sub_i32 m0, s53, m0
	s_add_i32 m0, m0, 0x20000
	s_nop 0
	global_load_lds_dword v250, s[98:99]
	global_load_lds_dword v250, s[98:99] offset:512
	v_and_b32_e32 v251, 31, v0
	v_bfe_u32 v252, v0, 5, 1
	v_lshl_add_u32 v251, v252, 7, v251
	v_lshlrev_b32_e32 v251, 2, v251
	s_mov_b32 s98, s15
	s_lshl_b32 s98, s98, 8
	s_add_i32 s98, s98, s59
	s_lshl_b32 s98, s98, 2
	s_add_u32 s98, s51, s98
	s_addc_u32 s99, s33, 0
	s_add_i32 m0, m0, 0x100
	s_nop 0
	global_load_lds_dword v251, s[98:99]
	s_add_u32 s8, s6, 0xfff80080
	s_addc_u32 s9, s7, -1
	s_add_i32 s45, 0, 0x10000
	s_cmp_eq_u32 s44, 28
	s_cselect_b32 s11, s12, s9
	s_cselect_b32 s10, s13, s8
	v_add_u32_e32 v2, s45, v194
	s_cselect_b32 s9, s27, s43
	s_cselect_b32 s8, s29, s42
	s_add_i32 s62, 0, 0x14000
	ds_read_b128 v[30:33], v2
	ds_read_b128 v[34:37], v2 offset:1024
	ds_read_b128 v[46:49], v2 offset:2048
	ds_read_b128 v[50:53], v2 offset:3072
	v_add_u32_e32 v2, s62, v194
	ds_read_b128 v[162:165], v2
	ds_read_b128 v[166:169], v2 offset:1024
	ds_read_b128 v[170:173], v2 offset:2048
	ds_read_b128 v[174:177], v2 offset:3072
	v_lshl_add_u64 v[4:5], s[6:7], 0, v[158:159]
	s_add_i32 m0, s53, 0xc000
	ds_read_b128 v[178:181], v195
	ds_read_b128 v[182:185], v195 offset:1024
	ds_read_b128 v[186:189], v195 offset:2048
	ds_read_b128 v[204:207], v195 offset:3072
	ds_read_b128 v[208:211], v195 offset:4096
	ds_read_b128 v[230:233], v195 offset:5120
	ds_read_b128 v[234:237], v195 offset:6144
	ds_read_b128 v[238:241], v195 offset:7168
	global_load_lds_dwordx4 v[4:5], off
	v_lshl_add_u64 v[4:5], s[6:7], 0, v[160:161]
	s_add_i32 m0, s53, 0xe000
	s_nop 0
	global_load_lds_dwordx4 v[4:5], off
	s_waitcnt vmcnt(11)
	s_waitcnt lgkmcnt(0)
	s_barrier
	v_mfma_i32_16x16x64_i8 v[146:149], v[30:33], v[178:181], 0
	v_mfma_i32_16x16x64_i8 v[142:145], v[46:49], v[178:181], 0
	v_mfma_i32_16x16x64_i8 v[130:133], v[30:33], v[186:189], 0
	v_mfma_i32_16x16x64_i8 v[126:129], v[46:49], v[186:189], 0
	v_mfma_i32_16x16x64_i8 v[114:117], v[30:33], v[208:211], 0
	v_mfma_i32_16x16x64_i8 v[110:113], v[46:49], v[208:211], 0
	v_mfma_i32_16x16x64_i8 v[98:101], v[30:33], v[234:237], 0
	v_mfma_i32_16x16x64_i8 v[94:97], v[46:49], v[234:237], 0
	v_mfma_i32_16x16x64_i8 v[146:149], v[34:37], v[182:185], v[146:149]
	v_mfma_i32_16x16x64_i8 v[142:145], v[50:53], v[182:185], v[142:145]
	v_mfma_i32_16x16x64_i8 v[130:133], v[34:37], v[204:207], v[130:133]
	v_mfma_i32_16x16x64_i8 v[126:129], v[50:53], v[204:207], v[126:129]
	v_mfma_i32_16x16x64_i8 v[114:117], v[34:37], v[230:233], v[114:117]
	v_mfma_i32_16x16x64_i8 v[110:113], v[50:53], v[230:233], v[110:113]
	v_mfma_i32_16x16x64_i8 v[98:101], v[34:37], v[238:241], v[98:101]
	v_mfma_i32_16x16x64_i8 v[94:97], v[50:53], v[238:241], v[94:97]
	v_mfma_i32_16x16x64_i8 v[138:141], v[162:165], v[178:181], 0
	v_mfma_i32_16x16x64_i8 v[134:137], v[170:173], v[178:181], 0
	v_mfma_i32_16x16x64_i8 v[122:125], v[162:165], v[186:189], 0
	v_mfma_i32_16x16x64_i8 v[118:121], v[170:173], v[186:189], 0
	v_mfma_i32_16x16x64_i8 v[106:109], v[162:165], v[208:211], 0
	v_mfma_i32_16x16x64_i8 v[102:105], v[170:173], v[208:211], 0
	v_mfma_i32_16x16x64_i8 v[90:93], v[162:165], v[234:237], 0
	v_mfma_i32_16x16x64_i8 v[86:89], v[170:173], v[234:237], 0
	v_mfma_i32_16x16x64_i8 v[138:141], v[166:169], v[182:185], v[138:141]
	v_mfma_i32_16x16x64_i8 v[134:137], v[174:177], v[182:185], v[134:137]
	v_mfma_i32_16x16x64_i8 v[122:125], v[166:169], v[204:207], v[122:125]
	v_mfma_i32_16x16x64_i8 v[118:121], v[174:177], v[204:207], v[118:121]
	v_mfma_i32_16x16x64_i8 v[106:109], v[166:169], v[230:233], v[106:109]
	v_mfma_i32_16x16x64_i8 v[102:105], v[174:177], v[230:233], v[102:105]
	v_mfma_i32_16x16x64_i8 v[90:93], v[166:169], v[238:241], v[90:93]
	v_mfma_i32_16x16x64_i8 v[86:89], v[174:177], v[238:241], v[86:89]
	s_barrier
	s_add_i32 s45, s45, s52
	v_lshl_add_u64 v[190:191], s[8:9], 0, v[154:155]
	s_mov_b32 m0, s45
	ds_read_b128 v[178:181], v195 offset:16384
	ds_read_b128 v[182:185], v195 offset:17408
	ds_read_b128 v[186:189], v195 offset:18432
	ds_read_b128 v[204:207], v195 offset:19456
	ds_read_b128 v[208:211], v195 offset:20480
	ds_read_b128 v[230:233], v195 offset:21504
	ds_read_b128 v[234:237], v195 offset:22528
	ds_read_b128 v[238:241], v195 offset:23552
	global_load_lds_dwordx4 v[190:191], off
	s_add_i32 m0, s45, 0x2000
	s_add_u32 s48, s8, 0x80000
	v_lshl_add_u64 v[196:197], s[8:9], 0, v[150:151]
	s_addc_u32 s49, s9, 0
	s_add_i32 s45, s62, s52
	global_load_lds_dwordx4 v[196:197], off
	v_lshl_add_u64 v[4:5], s[48:49], 0, v[154:155]
	s_mov_b32 m0, s45
	v_lshl_add_u64 v[198:199], s[10:11], 0, v[156:157]
	global_load_lds_dwordx4 v[4:5], off
	v_lshl_add_u64 v[4:5], s[48:49], 0, v[150:151]
	s_add_i32 m0, s45, 0x2000
	v_lshl_add_u64 v[212:213], s[10:11], 0, v[152:153]
	global_load_lds_dwordx4 v[4:5], off
	s_mov_b32 m0, s53
	s_nop 0
	global_load_lds_dwordx4 v[198:199], off
	s_mov_b32 m0, s54
	s_nop 0
	global_load_lds_dwordx4 v[212:213], off
	s_waitcnt vmcnt(11)
	s_waitcnt lgkmcnt(0)
	s_barrier
	v_mfma_i32_16x16x64_i8 v[82:85], v[30:33], v[178:181], 0
	v_mfma_i32_16x16x64_i8 v[78:81], v[46:49], v[178:181], 0
	v_mfma_i32_16x16x64_i8 v[66:69], v[30:33], v[186:189], 0
	v_mfma_i32_16x16x64_i8 v[62:65], v[46:49], v[186:189], 0
	v_mfma_i32_16x16x64_i8 v[42:45], v[30:33], v[208:211], 0
	v_mfma_i32_16x16x64_i8 v[38:41], v[46:49], v[208:211], 0
	v_mfma_i32_16x16x64_i8 v[18:21], v[30:33], v[234:237], 0
	v_mfma_i32_16x16x64_i8 v[14:17], v[46:49], v[234:237], 0
	v_mfma_i32_16x16x64_i8 v[82:85], v[34:37], v[182:185], v[82:85]
	v_mfma_i32_16x16x64_i8 v[78:81], v[50:53], v[182:185], v[78:81]
	v_mfma_i32_16x16x64_i8 v[66:69], v[34:37], v[204:207], v[66:69]
	v_mfma_i32_16x16x64_i8 v[62:65], v[50:53], v[204:207], v[62:65]
	v_mfma_i32_16x16x64_i8 v[42:45], v[34:37], v[230:233], v[42:45]
	v_mfma_i32_16x16x64_i8 v[38:41], v[50:53], v[230:233], v[38:41]
	v_mfma_i32_16x16x64_i8 v[18:21], v[34:37], v[238:241], v[18:21]
	v_mfma_i32_16x16x64_i8 v[14:17], v[50:53], v[238:241], v[14:17]
	v_mfma_i32_16x16x64_i8 v[26:29], v[162:165], v[208:211], 0
	v_mfma_i32_16x16x64_i8 v[22:25], v[170:173], v[208:211], 0
	v_mfma_i32_16x16x64_i8 v[10:13], v[162:165], v[234:237], 0
	v_mfma_i32_16x16x64_i8 v[4:7], v[170:173], v[234:237], 0
	v_mfma_i32_16x16x64_i8 v[30:33], v[162:165], v[178:181], 0
	v_mfma_i32_16x16x64_i8 v[34:37], v[170:173], v[178:181], 0
	v_mfma_i32_16x16x64_i8 v[46:49], v[162:165], v[186:189], 0
	v_mfma_i32_16x16x64_i8 v[50:53], v[170:173], v[186:189], 0
	v_mfma_i32_16x16x64_i8 v[26:29], v[166:169], v[230:233], v[26:29]
	v_mfma_i32_16x16x64_i8 v[22:25], v[174:177], v[230:233], v[22:25]
	v_mfma_i32_16x16x64_i8 v[10:13], v[166:169], v[238:241], v[10:13]
	v_mfma_i32_16x16x64_i8 v[4:7], v[174:177], v[238:241], v[4:7]
	v_mfma_i32_16x16x64_i8 v[30:33], v[166:169], v[182:185], v[30:33]
	v_mfma_i32_16x16x64_i8 v[34:37], v[174:177], v[182:185], v[34:37]
	v_mfma_i32_16x16x64_i8 v[46:49], v[166:169], v[204:207], v[46:49]
	v_mfma_i32_16x16x64_i8 v[50:53], v[174:177], v[204:207], v[50:53]
	s_barrier
	s_add_i32 s45, 0, 0x18000
	v_add_u32_e32 v2, s45, v194
	s_add_i32 s48, 0, 0x1c000
	ds_read_b128 v[54:57], v2
	ds_read_b128 v[58:61], v2 offset:1024
	ds_read_b128 v[70:73], v2 offset:2048
	ds_read_b128 v[74:77], v2 offset:3072
	v_add_u32_e32 v2, s48, v194
	ds_read_b128 v[162:165], v2
	ds_read_b128 v[166:169], v2 offset:1024
	ds_read_b128 v[170:173], v2 offset:2048
	ds_read_b128 v[174:177], v2 offset:3072
	s_add_u32 s10, s10, 0x80000
	s_addc_u32 s11, s11, 0
	s_mov_b32 m0, s55
	v_lshl_add_u64 v[8:9], s[10:11], 0, v[156:157]
	ds_read_b128 v[178:181], v195 offset:32768
	ds_read_b128 v[182:185], v195 offset:33792
	ds_read_b128 v[186:189], v195 offset:34816
	ds_read_b128 v[204:207], v195 offset:35840
	ds_read_b128 v[208:211], v195 offset:36864
	ds_read_b128 v[230:233], v195 offset:37888
	ds_read_b128 v[234:237], v195 offset:38912
	ds_read_b128 v[238:241], v195 offset:39936
	global_load_lds_dwordx4 v[8:9], off
	v_lshl_add_u64 v[8:9], s[10:11], 0, v[152:153]
	s_mov_b32 m0, s56
	s_nop 0
	global_load_lds_dwordx4 v[8:9], off
	s_waitcnt vmcnt(8)
	s_waitcnt lgkmcnt(0)
	s_barrier
	v_mfma_i32_16x16x64_i8 v[146:149], v[54:57], v[178:181], v[146:149]
	v_mfma_i32_16x16x64_i8 v[142:145], v[70:73], v[178:181], v[142:145]
	v_mfma_i32_16x16x64_i8 v[130:133], v[54:57], v[186:189], v[130:133]
	v_mfma_i32_16x16x64_i8 v[126:129], v[70:73], v[186:189], v[126:129]
	v_mfma_i32_16x16x64_i8 v[114:117], v[54:57], v[208:211], v[114:117]
	v_mfma_i32_16x16x64_i8 v[110:113], v[70:73], v[208:211], v[110:113]
	v_mfma_i32_16x16x64_i8 v[98:101], v[54:57], v[234:237], v[98:101]
	v_mfma_i32_16x16x64_i8 v[94:97], v[70:73], v[234:237], v[94:97]
	v_mfma_i32_16x16x64_i8 v[146:149], v[58:61], v[182:185], v[146:149]
	v_mfma_i32_16x16x64_i8 v[142:145], v[74:77], v[182:185], v[142:145]
	v_mfma_i32_16x16x64_i8 v[130:133], v[58:61], v[204:207], v[130:133]
	v_mfma_i32_16x16x64_i8 v[126:129], v[74:77], v[204:207], v[126:129]
	v_mfma_i32_16x16x64_i8 v[114:117], v[58:61], v[230:233], v[114:117]
	v_mfma_i32_16x16x64_i8 v[110:113], v[74:77], v[230:233], v[110:113]
	v_mfma_i32_16x16x64_i8 v[98:101], v[58:61], v[238:241], v[98:101]
	v_mfma_i32_16x16x64_i8 v[94:97], v[74:77], v[238:241], v[94:97]
	v_mfma_i32_16x16x64_i8 v[138:141], v[162:165], v[178:181], v[138:141]
	v_mfma_i32_16x16x64_i8 v[134:137], v[170:173], v[178:181], v[134:137]
	v_mfma_i32_16x16x64_i8 v[122:125], v[162:165], v[186:189], v[122:125]
	v_mfma_i32_16x16x64_i8 v[118:121], v[170:173], v[186:189], v[118:121]
	v_mfma_i32_16x16x64_i8 v[106:109], v[162:165], v[208:211], v[106:109]
	v_mfma_i32_16x16x64_i8 v[102:105], v[170:173], v[208:211], v[102:105]
	v_mfma_i32_16x16x64_i8 v[90:93], v[162:165], v[234:237], v[90:93]
	v_mfma_i32_16x16x64_i8 v[86:89], v[170:173], v[234:237], v[86:89]
	v_mfma_i32_16x16x64_i8 v[138:141], v[166:169], v[182:185], v[138:141]
	v_mfma_i32_16x16x64_i8 v[134:137], v[174:177], v[182:185], v[134:137]
	v_mfma_i32_16x16x64_i8 v[122:125], v[166:169], v[204:207], v[122:125]
	v_mfma_i32_16x16x64_i8 v[118:121], v[174:177], v[204:207], v[118:121]
	v_mfma_i32_16x16x64_i8 v[106:109], v[166:169], v[230:233], v[106:109]
	v_mfma_i32_16x16x64_i8 v[102:105], v[174:177], v[230:233], v[102:105]
	v_mfma_i32_16x16x64_i8 v[90:93], v[166:169], v[238:241], v[90:93]
	v_mfma_i32_16x16x64_i8 v[86:89], v[174:177], v[238:241], v[86:89]
	s_barrier
	s_add_i32 s10, s45, s52
	v_lshl_add_u64 v[8:9], v[190:191], 0, s[94:95]
	s_mov_b32 m0, s10
	ds_read_b128 v[178:181], v195 offset:49152
	ds_read_b128 v[182:185], v195 offset:50176
	ds_read_b128 v[186:189], v195 offset:51200
	ds_read_b128 v[204:207], v195 offset:52224
	ds_read_b128 v[208:211], v195 offset:53248
	ds_read_b128 v[230:233], v195 offset:54272
	ds_read_b128 v[234:237], v195 offset:55296
	ds_read_b128 v[238:241], v195 offset:56320
	global_load_lds_dwordx4 v[8:9], off
	s_add_i32 m0, s10, 0x2000
	s_add_u32 s8, s8, 0x80080
	v_lshl_add_u64 v[8:9], v[196:197], 0, s[94:95]
	s_addc_u32 s9, s9, 0
	s_add_i32 s10, s48, s52
	global_load_lds_dwordx4 v[8:9], off
	v_lshl_add_u64 v[8:9], s[8:9], 0, v[154:155]
	s_mov_b32 m0, s10
	s_nop 0
	global_load_lds_dwordx4 v[8:9], off
	v_lshl_add_u64 v[8:9], s[8:9], 0, v[150:151]
	s_add_i32 m0, s10, 0x2000
	s_nop 0
	global_load_lds_dwordx4 v[8:9], off
	v_lshl_add_u64 v[8:9], v[198:199], 0, s[94:95]
	s_mov_b32 m0, s71
	s_nop 0
	global_load_lds_dwordx4 v[8:9], off
	v_lshl_add_u64 v[8:9], v[212:213], 0, s[94:95]
	s_mov_b32 m0, s74
	s_nop 0
	global_load_lds_dwordx4 v[8:9], off
	s_waitcnt vmcnt(8)
	s_waitcnt lgkmcnt(0)
	s_barrier
	v_mfma_i32_16x16x64_i8 v[82:85], v[54:57], v[178:181], v[82:85]
	v_mfma_i32_16x16x64_i8 v[78:81], v[70:73], v[178:181], v[78:81]
	v_mfma_i32_16x16x64_i8 v[66:69], v[54:57], v[186:189], v[66:69]
	v_mfma_i32_16x16x64_i8 v[62:65], v[70:73], v[186:189], v[62:65]
	v_mfma_i32_16x16x64_i8 v[42:45], v[54:57], v[208:211], v[42:45]
	v_mfma_i32_16x16x64_i8 v[38:41], v[70:73], v[208:211], v[38:41]
	v_mfma_i32_16x16x64_i8 v[18:21], v[54:57], v[234:237], v[18:21]
	v_mfma_i32_16x16x64_i8 v[14:17], v[70:73], v[234:237], v[14:17]
	v_mfma_i32_16x16x64_i8 v[82:85], v[58:61], v[182:185], v[82:85]
	v_mfma_i32_16x16x64_i8 v[78:81], v[74:77], v[182:185], v[78:81]
	v_mfma_i32_16x16x64_i8 v[66:69], v[58:61], v[204:207], v[66:69]
	v_mfma_i32_16x16x64_i8 v[62:65], v[74:77], v[204:207], v[62:65]
	v_mfma_i32_16x16x64_i8 v[42:45], v[58:61], v[230:233], v[42:45]
	v_mfma_i32_16x16x64_i8 v[38:41], v[74:77], v[230:233], v[38:41]
	v_mfma_i32_16x16x64_i8 v[18:21], v[58:61], v[238:241], v[18:21]
	v_mfma_i32_16x16x64_i8 v[14:17], v[74:77], v[238:241], v[14:17]
	v_mfma_i32_16x16x64_i8 v[30:33], v[162:165], v[178:181], v[30:33]
	v_mfma_i32_16x16x64_i8 v[74:77], v[166:169], v[182:185], v[30:33]
	v_mfma_i32_16x16x64_i8 v[30:33], v[170:173], v[178:181], v[34:37]
	v_mfma_i32_16x16x64_i8 v[70:73], v[174:177], v[182:185], v[30:33]
	v_mfma_i32_16x16x64_i8 v[30:33], v[162:165], v[186:189], v[46:49]
	v_mfma_i32_16x16x64_i8 v[58:61], v[166:169], v[204:207], v[30:33]
	v_mfma_i32_16x16x64_i8 v[30:33], v[170:173], v[186:189], v[50:53]
	v_mfma_i32_16x16x64_i8 v[26:29], v[162:165], v[208:211], v[26:29]
	v_mfma_i32_16x16x64_i8 v[22:25], v[170:173], v[208:211], v[22:25]
	v_mfma_i32_16x16x64_i8 v[8:11], v[162:165], v[234:237], v[10:13]
	v_mfma_i32_16x16x64_i8 v[4:7], v[170:173], v[234:237], v[4:7]
	v_mfma_i32_16x16x64_i8 v[54:57], v[174:177], v[204:207], v[30:33]
	v_mfma_i32_16x16x64_i8 v[26:29], v[166:169], v[230:233], v[26:29]
	v_mfma_i32_16x16x64_i8 v[22:25], v[174:177], v[230:233], v[22:25]
	v_mfma_i32_16x16x64_i8 v[10:13], v[166:169], v[238:241], v[8:11]
	v_mfma_i32_16x16x64_i8 v[6:9], v[174:177], v[238:241], v[4:7]
	s_barrier
	s_add_i32 s44, s44, 2
	s_add_u32 s6, s6, 0x100
	s_addc_u32 s7, s7, 0
	s_add_u32 s42, s42, 0x100
	s_addc_u32 s43, s43, 0
	s_cmp_gt_u32 s44, 29

.LBB0_1202:
	s_ashr_i32 s19, s18, 31
	s_lshl_b64 s[20:21], s[18:19], 18
	s_add_u32 s20, s0, s20
	s_addc_u32 s21, s1, s21
	s_and_b64 s[22:23], s[4:5], exec
	s_cselect_b32 s19, s21, s25
	s_cselect_b32 s45, s20, s24
	s_ashr_i32 s17, s16, 31
	s_lshl_b64 s[22:23], s[16:17], 18
	s_add_u32 s22, s14, s22
	s_addc_u32 s23, s15, s23
	s_and_b64 s[28:29], s[4:5], exec
	s_cselect_b32 s17, s23, s27
	s_cselect_b32 s46, s22, s26
	s_add_u32 s24, s24, 0x20080
	s_addc_u32 s25, s25, 0
	s_add_u32 s47, s26, 0x100
	s_addc_u32 s48, s27, 0
	s_mov_b32 s49, -2
	s_lshl_b32 s98, s44, 8
	s_add_i32 s98, s98, s36
	v_add_u32_e32 v252, s98, v156
	v_ashrrev_i32_e32 v253, 31, v252
	v_lshl_add_u64 v[252:253], v[252:253], 3, s[12:13]
	global_load_dwordx2 v[238:239], v[252:253], off
	global_load_dwordx2 v[240:241], v[252:253], off offset:128
	global_load_dwordx2 v[242:243], v[252:253], off offset:256
	global_load_dwordx2 v[244:245], v[252:253], off offset:384
	global_load_dwordx2 v[246:247], v[252:253], off offset:1024
	global_load_dwordx2 v[248:249], v[252:253], off offset:1152
	global_load_dwordx2 v[250:251], v[252:253], off offset:1280
	global_load_dwordx2 v[226:227], v[252:253], off offset:1408
	s_add_u32 s26, s24, 0xfffe0080
	s_addc_u32 s27, s25, -1
	s_add_i32 s51, 0, 0x10000
	s_cmp_eq_u32 s49, 4
	s_cselect_b32 s29, s19, s27
	s_cselect_b32 s28, s45, s26
	v_add_u32_e32 v154, s51, v158
	s_cselect_b32 s27, s17, s48
	s_cselect_b32 s26, s46, s47
	s_add_i32 s54, 0, 0x14000
	ds_read_b128 v[142:145], v154
	ds_read_b128 v[146:149], v154 offset:1024
	ds_read_b128 v[150:153], v154 offset:2048
	ds_read_b128 v[160:163], v154 offset:3072
	v_add_u32_e32 v154, s54, v158
	ds_read_b128 v[164:167], v154
	ds_read_b128 v[168:171], v154 offset:1024
	ds_read_b128 v[172:175], v154 offset:2048
	ds_read_b128 v[176:179], v154 offset:3072
	v_lshl_add_u64 v[154:155], s[24:25], 0, v[138:139]
	s_add_i32 m0, s31, 0xc000
	ds_read_b128 v[180:183], v159
	ds_read_b128 v[184:187], v159 offset:1024
	ds_read_b128 v[188:191], v159 offset:2048
	ds_read_b128 v[192:195], v159 offset:3072
	ds_read_b128 v[204:207], v159 offset:4096
	ds_read_b128 v[208:211], v159 offset:5120
	ds_read_b128 v[230:233], v159 offset:6144
	ds_read_b128 v[234:237], v159 offset:7168
	global_load_lds_dwordx4 v[154:155], off
	v_lshl_add_u64 v[154:155], s[24:25], 0, v[140:141]
	s_add_i32 m0, s31, 0xe000
	s_nop 0
	global_load_lds_dwordx4 v[154:155], off
	s_waitcnt vmcnt(16)
	s_waitcnt lgkmcnt(0)
	s_barrier
	v_mfma_f32_16x16x32_bf16 v[128:131], v[142:145], v[180:183], 0
	v_mfma_f32_16x16x32_bf16 v[124:127], v[150:153], v[180:183], 0
	v_mfma_f32_16x16x32_bf16 v[112:115], v[142:145], v[188:191], 0
	v_mfma_f32_16x16x32_bf16 v[108:111], v[150:153], v[188:191], 0
	v_mfma_f32_16x16x32_bf16 v[96:99], v[142:145], v[204:207], 0
	v_mfma_f32_16x16x32_bf16 v[92:95], v[150:153], v[204:207], 0
	v_mfma_f32_16x16x32_bf16 v[80:83], v[142:145], v[230:233], 0
	v_mfma_f32_16x16x32_bf16 v[76:79], v[150:153], v[230:233], 0
	v_mfma_f32_16x16x32_bf16 v[128:131], v[146:149], v[184:187], v[128:131]
	v_mfma_f32_16x16x32_bf16 v[124:127], v[160:163], v[184:187], v[124:127]
	v_mfma_f32_16x16x32_bf16 v[112:115], v[146:149], v[192:195], v[112:115]
	v_mfma_f32_16x16x32_bf16 v[108:111], v[160:163], v[192:195], v[108:111]
	v_mfma_f32_16x16x32_bf16 v[96:99], v[146:149], v[208:211], v[96:99]
	v_mfma_f32_16x16x32_bf16 v[92:95], v[160:163], v[208:211], v[92:95]
	v_mfma_f32_16x16x32_bf16 v[80:83], v[146:149], v[234:237], v[80:83]
	v_mfma_f32_16x16x32_bf16 v[76:79], v[160:163], v[234:237], v[76:79]
	v_mfma_f32_16x16x32_bf16 v[120:123], v[164:167], v[180:183], 0
	v_mfma_f32_16x16x32_bf16 v[116:119], v[172:175], v[180:183], 0
	v_mfma_f32_16x16x32_bf16 v[104:107], v[164:167], v[188:191], 0
	v_mfma_f32_16x16x32_bf16 v[100:103], v[172:175], v[188:191], 0
	v_mfma_f32_16x16x32_bf16 v[88:91], v[164:167], v[204:207], 0
	v_mfma_f32_16x16x32_bf16 v[84:87], v[172:175], v[204:207], 0
	v_mfma_f32_16x16x32_bf16 v[72:75], v[164:167], v[230:233], 0
	v_mfma_f32_16x16x32_bf16 v[68:71], v[172:175], v[230:233], 0
	v_mfma_f32_16x16x32_bf16 v[120:123], v[168:171], v[184:187], v[120:123]
	v_mfma_f32_16x16x32_bf16 v[116:119], v[176:179], v[184:187], v[116:119]
	v_mfma_f32_16x16x32_bf16 v[104:107], v[168:171], v[192:195], v[104:107]
	v_mfma_f32_16x16x32_bf16 v[100:103], v[176:179], v[192:195], v[100:103]
	v_mfma_f32_16x16x32_bf16 v[88:91], v[168:171], v[208:211], v[88:91]
	v_mfma_f32_16x16x32_bf16 v[84:87], v[176:179], v[208:211], v[84:87]
	v_mfma_f32_16x16x32_bf16 v[72:75], v[168:171], v[234:237], v[72:75]
	v_mfma_f32_16x16x32_bf16 v[68:71], v[176:179], v[234:237], v[68:71]
	s_barrier
	s_add_i32 s51, s51, s30
	v_lshl_add_u64 v[154:155], s[26:27], 0, v[2:3]
	s_mov_b32 m0, s51
	ds_read_b128 v[180:183], v159 offset:16384
	ds_read_b128 v[184:187], v159 offset:17408
	ds_read_b128 v[188:191], v159 offset:18432
	ds_read_b128 v[192:195], v159 offset:19456
	ds_read_b128 v[204:207], v159 offset:20480
	ds_read_b128 v[208:211], v159 offset:21504
	ds_read_b128 v[230:233], v159 offset:22528
	ds_read_b128 v[234:237], v159 offset:23552
	global_load_lds_dwordx4 v[154:155], off
	s_add_i32 m0, s51, 0x2000
	s_add_u32 s52, s26, 0x20000
	v_lshl_add_u64 v[196:197], s[26:27], 0, v[132:133]
	s_addc_u32 s53, s27, 0
	s_add_i32 s51, s54, s30
	global_load_lds_dwordx4 v[196:197], off
	v_lshl_add_u64 v[198:199], s[52:53], 0, v[2:3]
	s_mov_b32 m0, s51
	v_lshl_add_u64 v[212:213], s[28:29], 0, v[134:135]
	global_load_lds_dwordx4 v[198:199], off
	v_lshl_add_u64 v[198:199], s[52:53], 0, v[132:133]
	s_add_i32 m0, s51, 0x2000
	s_nop 0
	global_load_lds_dwordx4 v[198:199], off
	v_lshl_add_u64 v[198:199], s[28:29], 0, v[136:137]
	s_mov_b32 m0, s31
	s_nop 0
	global_load_lds_dwordx4 v[198:199], off
	s_mov_b32 m0, s33
	s_nop 0
	global_load_lds_dwordx4 v[212:213], off
	s_waitcnt vmcnt(16)
	s_waitcnt lgkmcnt(0)
	s_barrier
	v_mfma_f32_16x16x32_bf16 v[64:67], v[142:145], v[180:183], 0
	v_mfma_f32_16x16x32_bf16 v[60:63], v[150:153], v[180:183], 0
	v_mfma_f32_16x16x32_bf16 v[48:51], v[142:145], v[188:191], 0
	v_mfma_f32_16x16x32_bf16 v[44:47], v[150:153], v[188:191], 0
	v_mfma_f32_16x16x32_bf16 v[32:35], v[142:145], v[204:207], 0
	v_mfma_f32_16x16x32_bf16 v[28:31], v[150:153], v[204:207], 0
	v_mfma_f32_16x16x32_bf16 v[16:19], v[142:145], v[230:233], 0
	v_mfma_f32_16x16x32_bf16 v[12:15], v[150:153], v[230:233], 0
	v_mfma_f32_16x16x32_bf16 v[64:67], v[146:149], v[184:187], v[64:67]
	v_mfma_f32_16x16x32_bf16 v[60:63], v[160:163], v[184:187], v[60:63]
	v_mfma_f32_16x16x32_bf16 v[48:51], v[146:149], v[192:195], v[48:51]
	v_mfma_f32_16x16x32_bf16 v[44:47], v[160:163], v[192:195], v[44:47]
	v_mfma_f32_16x16x32_bf16 v[32:35], v[146:149], v[208:211], v[32:35]
	v_mfma_f32_16x16x32_bf16 v[28:31], v[160:163], v[208:211], v[28:31]
	v_mfma_f32_16x16x32_bf16 v[16:19], v[146:149], v[234:237], v[16:19]
	v_mfma_f32_16x16x32_bf16 v[12:15], v[160:163], v[234:237], v[12:15]
	v_mfma_f32_16x16x32_bf16 v[56:59], v[164:167], v[180:183], 0
	v_mfma_f32_16x16x32_bf16 v[52:55], v[172:175], v[180:183], 0
	v_mfma_f32_16x16x32_bf16 v[40:43], v[164:167], v[188:191], 0
	v_mfma_f32_16x16x32_bf16 v[36:39], v[172:175], v[188:191], 0
	v_mfma_f32_16x16x32_bf16 v[24:27], v[164:167], v[204:207], 0
	v_mfma_f32_16x16x32_bf16 v[20:23], v[172:175], v[204:207], 0
	v_mfma_f32_16x16x32_bf16 v[8:11], v[164:167], v[230:233], 0
	v_mfma_f32_16x16x32_bf16 v[4:7], v[172:175], v[230:233], 0
	v_mfma_f32_16x16x32_bf16 v[56:59], v[168:171], v[184:187], v[56:59]
	v_mfma_f32_16x16x32_bf16 v[52:55], v[176:179], v[184:187], v[52:55]
	v_mfma_f32_16x16x32_bf16 v[40:43], v[168:171], v[192:195], v[40:43]
	v_mfma_f32_16x16x32_bf16 v[36:39], v[176:179], v[192:195], v[36:39]
	v_mfma_f32_16x16x32_bf16 v[24:27], v[168:171], v[208:211], v[24:27]
	v_mfma_f32_16x16x32_bf16 v[20:23], v[176:179], v[208:211], v[20:23]
	v_mfma_f32_16x16x32_bf16 v[8:11], v[168:171], v[234:237], v[8:11]
	v_mfma_f32_16x16x32_bf16 v[4:7], v[176:179], v[234:237], v[4:7]
	s_barrier
	s_add_i32 s51, 0, 0x18000
	s_add_i32 s52, 0, 0x1c000
	v_add_u32_e32 v160, s51, v158
	v_add_u32_e32 v176, s52, v158
	ds_read_b128 v[142:145], v160
	ds_read_b128 v[146:149], v160 offset:1024
	ds_read_b128 v[150:153], v160 offset:2048
	ds_read_b128 v[160:163], v160 offset:3072
	ds_read_b128 v[164:167], v176
	ds_read_b128 v[168:171], v176 offset:1024
	ds_read_b128 v[172:175], v176 offset:2048
	ds_read_b128 v[176:179], v176 offset:3072
	s_add_u32 s28, s28, 0x20000
	s_addc_u32 s29, s29, 0
	s_mov_b32 m0, s34
	v_lshl_add_u64 v[214:215], s[28:29], 0, v[136:137]
	ds_read_b128 v[180:183], v159 offset:32768
	ds_read_b128 v[184:187], v159 offset:33792
	ds_read_b128 v[188:191], v159 offset:34816
	ds_read_b128 v[192:195], v159 offset:35840
	ds_read_b128 v[204:207], v159 offset:36864
	ds_read_b128 v[208:211], v159 offset:37888
	ds_read_b128 v[230:233], v159 offset:38912
	ds_read_b128 v[234:237], v159 offset:39936
	global_load_lds_dwordx4 v[214:215], off
	v_lshl_add_u64 v[214:215], s[28:29], 0, v[134:135]
	s_mov_b32 m0, s35
	s_nop 0
	global_load_lds_dwordx4 v[214:215], off
	s_waitcnt vmcnt(8)
	s_waitcnt lgkmcnt(0)
	s_barrier
	v_mfma_f32_16x16x32_bf16 v[128:131], v[142:145], v[180:183], v[128:131]
	v_mfma_f32_16x16x32_bf16 v[124:127], v[150:153], v[180:183], v[124:127]
	v_mfma_f32_16x16x32_bf16 v[112:115], v[142:145], v[188:191], v[112:115]
	v_mfma_f32_16x16x32_bf16 v[108:111], v[150:153], v[188:191], v[108:111]
	v_mfma_f32_16x16x32_bf16 v[96:99], v[142:145], v[204:207], v[96:99]
	v_mfma_f32_16x16x32_bf16 v[92:95], v[150:153], v[204:207], v[92:95]
	v_mfma_f32_16x16x32_bf16 v[80:83], v[142:145], v[230:233], v[80:83]
	v_mfma_f32_16x16x32_bf16 v[76:79], v[150:153], v[230:233], v[76:79]
	v_mfma_f32_16x16x32_bf16 v[128:131], v[146:149], v[184:187], v[128:131]
	v_mfma_f32_16x16x32_bf16 v[124:127], v[160:163], v[184:187], v[124:127]
	v_mfma_f32_16x16x32_bf16 v[112:115], v[146:149], v[192:195], v[112:115]
	v_mfma_f32_16x16x32_bf16 v[108:111], v[160:163], v[192:195], v[108:111]
	v_mfma_f32_16x16x32_bf16 v[96:99], v[146:149], v[208:211], v[96:99]
	v_mfma_f32_16x16x32_bf16 v[92:95], v[160:163], v[208:211], v[92:95]
	v_mfma_f32_16x16x32_bf16 v[80:83], v[146:149], v[234:237], v[80:83]
	v_mfma_f32_16x16x32_bf16 v[76:79], v[160:163], v[234:237], v[76:79]
	v_mfma_f32_16x16x32_bf16 v[120:123], v[164:167], v[180:183], v[120:123]
	v_mfma_f32_16x16x32_bf16 v[116:119], v[172:175], v[180:183], v[116:119]
	v_mfma_f32_16x16x32_bf16 v[104:107], v[164:167], v[188:191], v[104:107]
	v_mfma_f32_16x16x32_bf16 v[100:103], v[172:175], v[188:191], v[100:103]
	v_mfma_f32_16x16x32_bf16 v[88:91], v[164:167], v[204:207], v[88:91]
	v_mfma_f32_16x16x32_bf16 v[84:87], v[172:175], v[204:207], v[84:87]
	v_mfma_f32_16x16x32_bf16 v[72:75], v[164:167], v[230:233], v[72:75]
	v_mfma_f32_16x16x32_bf16 v[68:71], v[172:175], v[230:233], v[68:71]
	v_mfma_f32_16x16x32_bf16 v[120:123], v[168:171], v[184:187], v[120:123]
	v_mfma_f32_16x16x32_bf16 v[116:119], v[176:179], v[184:187], v[116:119]
	v_mfma_f32_16x16x32_bf16 v[104:107], v[168:171], v[192:195], v[104:107]
	v_mfma_f32_16x16x32_bf16 v[100:103], v[176:179], v[192:195], v[100:103]
	v_mfma_f32_16x16x32_bf16 v[88:91], v[168:171], v[208:211], v[88:91]
	v_mfma_f32_16x16x32_bf16 v[84:87], v[176:179], v[208:211], v[84:87]
	v_mfma_f32_16x16x32_bf16 v[72:75], v[168:171], v[234:237], v[72:75]
	v_mfma_f32_16x16x32_bf16 v[68:71], v[176:179], v[234:237], v[68:71]
	s_barrier
	s_add_i32 s28, s51, s30
	v_lshl_add_u64 v[154:155], v[154:155], 0, s[94:95]
	s_mov_b32 m0, s28
	ds_read_b128 v[180:183], v159 offset:49152
	ds_read_b128 v[184:187], v159 offset:50176
	ds_read_b128 v[188:191], v159 offset:51200
	ds_read_b128 v[192:195], v159 offset:52224
	ds_read_b128 v[204:207], v159 offset:53248
	ds_read_b128 v[208:211], v159 offset:54272
	ds_read_b128 v[230:233], v159 offset:55296
	ds_read_b128 v[234:237], v159 offset:56320
	global_load_lds_dwordx4 v[154:155], off
	s_add_i32 m0, s28, 0x2000
	s_add_u32 s26, s26, 0x20080
	v_lshl_add_u64 v[154:155], v[196:197], 0, s[94:95]
	s_addc_u32 s27, s27, 0
	s_add_i32 s28, s52, s30
	global_load_lds_dwordx4 v[154:155], off
	v_lshl_add_u64 v[154:155], s[26:27], 0, v[2:3]
	s_mov_b32 m0, s28
	s_nop 0
	global_load_lds_dwordx4 v[154:155], off
	v_lshl_add_u64 v[154:155], s[26:27], 0, v[132:133]
	s_add_i32 m0, s28, 0x2000
	s_nop 0
	global_load_lds_dwordx4 v[154:155], off
	v_lshl_add_u64 v[154:155], v[198:199], 0, s[94:95]
	s_mov_b32 m0, s39
	s_nop 0
	global_load_lds_dwordx4 v[154:155], off
	v_lshl_add_u64 v[154:155], v[212:213], 0, s[94:95]
	s_mov_b32 m0, s40
	s_nop 0
	global_load_lds_dwordx4 v[154:155], off
	s_waitcnt vmcnt(8)
	s_waitcnt lgkmcnt(0)
	s_barrier
	v_mfma_f32_16x16x32_bf16 v[64:67], v[142:145], v[180:183], v[64:67]
	v_mfma_f32_16x16x32_bf16 v[60:63], v[150:153], v[180:183], v[60:63]
	v_mfma_f32_16x16x32_bf16 v[48:51], v[142:145], v[188:191], v[48:51]
	v_mfma_f32_16x16x32_bf16 v[44:47], v[150:153], v[188:191], v[44:47]
	v_mfma_f32_16x16x32_bf16 v[32:35], v[142:145], v[204:207], v[32:35]
	v_mfma_f32_16x16x32_bf16 v[28:31], v[150:153], v[204:207], v[28:31]
	v_mfma_f32_16x16x32_bf16 v[16:19], v[142:145], v[230:233], v[16:19]
	v_mfma_f32_16x16x32_bf16 v[12:15], v[150:153], v[230:233], v[12:15]
	v_mfma_f32_16x16x32_bf16 v[64:67], v[146:149], v[184:187], v[64:67]
	v_mfma_f32_16x16x32_bf16 v[60:63], v[160:163], v[184:187], v[60:63]
	v_mfma_f32_16x16x32_bf16 v[48:51], v[146:149], v[192:195], v[48:51]
	v_mfma_f32_16x16x32_bf16 v[44:47], v[160:163], v[192:195], v[44:47]
	v_mfma_f32_16x16x32_bf16 v[32:35], v[146:149], v[208:211], v[32:35]
	v_mfma_f32_16x16x32_bf16 v[28:31], v[160:163], v[208:211], v[28:31]
	v_mfma_f32_16x16x32_bf16 v[16:19], v[146:149], v[234:237], v[16:19]
	v_mfma_f32_16x16x32_bf16 v[12:15], v[160:163], v[234:237], v[12:15]
	v_mfma_f32_16x16x32_bf16 v[56:59], v[164:167], v[180:183], v[56:59]
	v_mfma_f32_16x16x32_bf16 v[52:55], v[172:175], v[180:183], v[52:55]
	v_mfma_f32_16x16x32_bf16 v[40:43], v[164:167], v[188:191], v[40:43]
	v_mfma_f32_16x16x32_bf16 v[36:39], v[172:175], v[188:191], v[36:39]
	v_mfma_f32_16x16x32_bf16 v[24:27], v[164:167], v[204:207], v[24:27]
	v_mfma_f32_16x16x32_bf16 v[20:23], v[172:175], v[204:207], v[20:23]
	v_mfma_f32_16x16x32_bf16 v[8:11], v[164:167], v[230:233], v[8:11]
	v_mfma_f32_16x16x32_bf16 v[4:7], v[172:175], v[230:233], v[4:7]
	v_mfma_f32_16x16x32_bf16 v[56:59], v[168:171], v[184:187], v[56:59]
	v_mfma_f32_16x16x32_bf16 v[52:55], v[176:179], v[184:187], v[52:55]
	v_mfma_f32_16x16x32_bf16 v[40:43], v[168:171], v[192:195], v[40:43]
	v_mfma_f32_16x16x32_bf16 v[36:39], v[176:179], v[192:195], v[36:39]
	v_mfma_f32_16x16x32_bf16 v[24:27], v[168:171], v[208:211], v[24:27]
	v_mfma_f32_16x16x32_bf16 v[20:23], v[176:179], v[208:211], v[20:23]
	v_mfma_f32_16x16x32_bf16 v[8:11], v[168:171], v[234:237], v[8:11]
	v_mfma_f32_16x16x32_bf16 v[4:7], v[176:179], v[234:237], v[4:7]
	s_barrier
	s_add_i32 s49, s49, 2
	s_add_u32 s24, s24, 0x100
	s_addc_u32 s25, s25, 0
	s_add_u32 s47, s47, 0x100
	s_addc_u32 s48, s48, 0
	s_cmp_gt_u32 s49, 5

.LBB0_1206:
	s_lshl_b32 s17, s44, 8
	v_mov_b32_e32 v142, v156
	v_mov_b32_e32 v164, v157
	s_add_i32 s17, s17, s36
	s_cmp_lt_i32 s43, 8
	v_add_u32_e32 v146, s17, v142
	v_ashrrev_i32_e32 v147, 31, v146
	v_lshl_add_u64 v[142:143], v[146:147], 3, s[12:13]
	s_nop 0
	s_nop 0
	s_nop 0
	s_nop 0
	s_nop 0
	s_nop 0
	s_nop 0
	s_nop 0
	s_nop 0
	s_mov_b32 s17, 0x3a800000
	s_cselect_b32 s17, s17, 0x3e800000
	s_lshl_b32 s19, s43, 8
	s_add_u32 s24, s6, s17
	s_addc_u32 s25, s7, 0
	s_and_b32 s17, s19, 0x700
	s_or_b32 s17, s17, s37
	v_lshl_add_u32 v164, v164, 3, s17
	v_ashrrev_i32_e32 v165, 31, v164
	v_lshl_add_u64 v[164:165], v[164:165], 1, s[24:25]
	v_lshlrev_b64 v[146:147], 12, v[146:147]
	v_lshl_add_u64 v[146:147], v[164:165], 0, v[146:147]
	s_mov_b32 s17, 0x10000
	s_mov_b64 s[24:25], 0x20000
	s_nop 0
	v_ffbh_u32_e32 v166, v239
	v_min_u32_e32 v166, 32, v166
	v_lshlrev_b64 v[160:161], v166, v[238:239]
	v_min_u32_e32 v160, 1, v160
	v_or_b32_e32 v160, v161, v160
	v_cvt_f32_u32_e32 v160, v160
	v_sub_u32_e32 v161, 32, v166
	v_ldexp_f32 v160, v160, v161
	v_fmamk_f32 v160, v160, 0x2b000000, v217
	v_rsq_f32_e32 v160, v160
	s_nop 0
	v_pk_mul_f32 v[130:131], v[130:131], v[160:161] op_sel_hi:[1,0]
	v_pk_mul_f32 v[128:129], v[128:129], v[160:161] op_sel_hi:[1,0]
	v_pk_mul_f32 v[164:165], v[126:127], v[160:161] op_sel_hi:[1,0]
	v_pk_mul_f32 v[126:127], v[124:125], v[160:161] op_sel_hi:[1,0]
	v_cvt_pk_bf16_f32 v124, v128, v129
	v_cvt_pk_bf16_f32 v125, v130, v131
	v_cvt_pk_bf16_f32 v126, v126, v127
	v_cvt_pk_bf16_f32 v127, v164, v165
	global_store_dwordx4 v[146:147], v[124:127], off
	v_pk_mul_f32 v[122:123], v[122:123], v[160:161] op_sel_hi:[1,0]
	v_pk_mul_f32 v[120:121], v[120:121], v[160:161] op_sel_hi:[1,0]
	v_pk_mul_f32 v[124:125], v[118:119], v[160:161] op_sel_hi:[1,0]
	v_pk_mul_f32 v[118:119], v[116:117], v[160:161] op_sel_hi:[1,0]
	v_cvt_pk_bf16_f32 v116, v120, v121
	v_cvt_pk_bf16_f32 v117, v122, v123
	v_cvt_pk_bf16_f32 v118, v118, v119
	v_cvt_pk_bf16_f32 v119, v124, v125
	global_store_dwordx4 v[146:147], v[116:119], off offset:256
	s_nop 1
	v_ffbh_u32_e32 v116, v241
	v_min_u32_e32 v118, 32, v116
	v_lshlrev_b64 v[116:117], v118, v[240:241]
	v_min_u32_e32 v116, 1, v116
	v_or_b32_e32 v116, v117, v116
	v_cvt_f32_u32_e32 v116, v116
	v_sub_u32_e32 v117, 32, v118
	v_lshl_add_u64 v[118:119], v[146:147], 0, s[56:57]
	v_ldexp_f32 v116, v116, v117
	v_fmamk_f32 v116, v116, 0x2b000000, v217
	v_rsq_f32_e32 v116, v116
	s_nop 0
	v_pk_mul_f32 v[112:113], v[112:113], v[116:117] op_sel_hi:[1,0]
	v_pk_mul_f32 v[114:115], v[114:115], v[116:117] op_sel_hi:[1,0]
	v_pk_mul_f32 v[120:121], v[110:111], v[116:117] op_sel_hi:[1,0]
	v_pk_mul_f32 v[110:111], v[108:109], v[116:117] op_sel_hi:[1,0]
	v_cvt_pk_bf16_f32 v108, v112, v113
	v_add_co_u32_e32 v112, vcc, s17, v146
	v_cvt_pk_bf16_f32 v109, v114, v115
	v_cvt_pk_bf16_f32 v110, v110, v111
	v_cvt_pk_bf16_f32 v111, v120, v121
	v_addc_co_u32_e32 v113, vcc, 0, v147, vcc
	global_store_dwordx4 v[112:113], v[108:111], off
	v_pk_mul_f32 v[106:107], v[106:107], v[116:117] op_sel_hi:[1,0]
	v_pk_mul_f32 v[104:105], v[104:105], v[116:117] op_sel_hi:[1,0]
	v_pk_mul_f32 v[108:109], v[102:103], v[116:117] op_sel_hi:[1,0]
	v_pk_mul_f32 v[102:103], v[100:101], v[116:117] op_sel_hi:[1,0]
	v_cvt_pk_bf16_f32 v100, v104, v105
	v_cvt_pk_bf16_f32 v101, v106, v107
	v_cvt_pk_bf16_f32 v102, v102, v103
	v_cvt_pk_bf16_f32 v103, v108, v109
	global_store_dwordx4 v[118:119], v[100:103], off offset:256
	s_mov_b32 s17, 0x20000
	s_nop 0
	v_ffbh_u32_e32 v100, v243
	v_min_u32_e32 v102, 32, v100
	v_lshlrev_b64 v[100:101], v102, v[242:243]
	v_min_u32_e32 v100, 1, v100
	v_or_b32_e32 v100, v101, v100
	v_cvt_f32_u32_e32 v100, v100
	v_sub_u32_e32 v101, 32, v102
	v_lshl_add_u64 v[102:103], v[146:147], 0, s[24:25]
	s_mov_b64 s[24:25], 0x30000
	v_ldexp_f32 v100, v100, v101
	v_fmamk_f32 v100, v100, 0x2b000000, v217
	v_rsq_f32_e32 v100, v100
	s_nop 0
	v_pk_mul_f32 v[96:97], v[96:97], v[100:101] op_sel_hi:[1,0]
	v_pk_mul_f32 v[98:99], v[98:99], v[100:101] op_sel_hi:[1,0]
	v_pk_mul_f32 v[104:105], v[94:95], v[100:101] op_sel_hi:[1,0]
	v_pk_mul_f32 v[94:95], v[92:93], v[100:101] op_sel_hi:[1,0]
	v_cvt_pk_bf16_f32 v92, v96, v97
	v_add_co_u32_e32 v96, vcc, s17, v146
	v_cvt_pk_bf16_f32 v93, v98, v99
	v_cvt_pk_bf16_f32 v94, v94, v95
	v_cvt_pk_bf16_f32 v95, v104, v105
	v_addc_co_u32_e32 v97, vcc, 0, v147, vcc
	global_store_dwordx4 v[96:97], v[92:95], off
	v_pk_mul_f32 v[90:91], v[90:91], v[100:101] op_sel_hi:[1,0]
	v_pk_mul_f32 v[88:89], v[88:89], v[100:101] op_sel_hi:[1,0]
	v_pk_mul_f32 v[92:93], v[86:87], v[100:101] op_sel_hi:[1,0]
	v_pk_mul_f32 v[86:87], v[84:85], v[100:101] op_sel_hi:[1,0]
	v_cvt_pk_bf16_f32 v84, v88, v89
	v_cvt_pk_bf16_f32 v85, v90, v91
	v_cvt_pk_bf16_f32 v86, v86, v87
	v_cvt_pk_bf16_f32 v87, v92, v93
	global_store_dwordx4 v[102:103], v[84:87], off offset:256
	s_mov_b32 s17, 0x30000
	s_nop 0
	v_ffbh_u32_e32 v84, v245
	v_min_u32_e32 v86, 32, v84
	v_lshlrev_b64 v[84:85], v86, v[244:245]
	v_min_u32_e32 v84, 1, v84
	v_or_b32_e32 v84, v85, v84
	v_cvt_f32_u32_e32 v84, v84
	v_sub_u32_e32 v85, 32, v86
	v_lshl_add_u64 v[86:87], v[146:147], 0, s[24:25]
	s_mov_b64 s[24:25], 0x80000
	v_ldexp_f32 v84, v84, v85
	v_fmamk_f32 v84, v84, 0x2b000000, v217
	v_rsq_f32_e32 v84, v84
	s_nop 0
	v_pk_mul_f32 v[80:81], v[80:81], v[84:85] op_sel_hi:[1,0]
	v_pk_mul_f32 v[82:83], v[82:83], v[84:85] op_sel_hi:[1,0]
	v_pk_mul_f32 v[88:89], v[78:79], v[84:85] op_sel_hi:[1,0]
	v_pk_mul_f32 v[78:79], v[76:77], v[84:85] op_sel_hi:[1,0]
	v_cvt_pk_bf16_f32 v76, v80, v81
	v_add_co_u32_e32 v80, vcc, s17, v146
	v_cvt_pk_bf16_f32 v77, v82, v83
	v_cvt_pk_bf16_f32 v78, v78, v79
	v_cvt_pk_bf16_f32 v79, v88, v89
	v_addc_co_u32_e32 v81, vcc, 0, v147, vcc
	global_store_dwordx4 v[80:81], v[76:79], off
	v_pk_mul_f32 v[74:75], v[74:75], v[84:85] op_sel_hi:[1,0]
	v_pk_mul_f32 v[72:73], v[72:73], v[84:85] op_sel_hi:[1,0]
	v_pk_mul_f32 v[76:77], v[70:71], v[84:85] op_sel_hi:[1,0]
	v_pk_mul_f32 v[70:71], v[68:69], v[84:85] op_sel_hi:[1,0]
	v_cvt_pk_bf16_f32 v68, v72, v73
	v_cvt_pk_bf16_f32 v69, v74, v75
	v_cvt_pk_bf16_f32 v70, v70, v71
	v_cvt_pk_bf16_f32 v71, v76, v77
	global_store_dwordx4 v[86:87], v[68:71], off offset:256
	s_mov_b32 s17, 0x80000
	s_nop 0
	v_ffbh_u32_e32 v68, v247
	v_min_u32_e32 v70, 32, v68
	v_lshlrev_b64 v[68:69], v70, v[246:247]
	v_min_u32_e32 v68, 1, v68
	v_or_b32_e32 v68, v69, v68
	v_cvt_f32_u32_e32 v68, v68
	v_sub_u32_e32 v69, 32, v70
	v_lshl_add_u64 v[70:71], v[146:147], 0, s[24:25]
	s_mov_b64 s[24:25], 0x90000
	v_ldexp_f32 v68, v68, v69
	v_fmamk_f32 v68, v68, 0x2b000000, v217
	v_rsq_f32_e32 v68, v68
	s_nop 0
	v_pk_mul_f32 v[64:65], v[64:65], v[68:69] op_sel_hi:[1,0]
	v_pk_mul_f32 v[66:67], v[66:67], v[68:69] op_sel_hi:[1,0]
	v_pk_mul_f32 v[72:73], v[62:63], v[68:69] op_sel_hi:[1,0]
	v_pk_mul_f32 v[62:63], v[60:61], v[68:69] op_sel_hi:[1,0]
	v_cvt_pk_bf16_f32 v60, v64, v65
	v_add_co_u32_e32 v64, vcc, s17, v146
	v_cvt_pk_bf16_f32 v61, v66, v67
	v_cvt_pk_bf16_f32 v62, v62, v63
	v_cvt_pk_bf16_f32 v63, v72, v73
	v_addc_co_u32_e32 v65, vcc, 0, v147, vcc
	global_store_dwordx4 v[64:65], v[60:63], off
	v_pk_mul_f32 v[58:59], v[58:59], v[68:69] op_sel_hi:[1,0]
	v_pk_mul_f32 v[56:57], v[56:57], v[68:69] op_sel_hi:[1,0]
	v_pk_mul_f32 v[60:61], v[54:55], v[68:69] op_sel_hi:[1,0]
	v_pk_mul_f32 v[54:55], v[52:53], v[68:69] op_sel_hi:[1,0]
	v_cvt_pk_bf16_f32 v52, v56, v57
	v_cvt_pk_bf16_f32 v53, v58, v59
	v_cvt_pk_bf16_f32 v54, v54, v55
	v_cvt_pk_bf16_f32 v55, v60, v61
	global_store_dwordx4 v[70:71], v[52:55], off offset:256
	s_mov_b32 s17, 0x90000
	s_nop 0
	v_ffbh_u32_e32 v52, v249
	v_min_u32_e32 v54, 32, v52
	v_lshlrev_b64 v[52:53], v54, v[248:249]
	v_min_u32_e32 v52, 1, v52
	v_or_b32_e32 v52, v53, v52
	v_cvt_f32_u32_e32 v52, v52
	v_sub_u32_e32 v53, 32, v54
	v_lshl_add_u64 v[54:55], v[146:147], 0, s[24:25]
	s_mov_b64 s[24:25], 0xa0000
	v_ldexp_f32 v52, v52, v53
	v_fmamk_f32 v52, v52, 0x2b000000, v217
	v_rsq_f32_e32 v52, v52
	s_nop 0
	v_pk_mul_f32 v[48:49], v[48:49], v[52:53] op_sel_hi:[1,0]
	v_pk_mul_f32 v[50:51], v[50:51], v[52:53] op_sel_hi:[1,0]
	v_pk_mul_f32 v[56:57], v[46:47], v[52:53] op_sel_hi:[1,0]
	v_pk_mul_f32 v[46:47], v[44:45], v[52:53] op_sel_hi:[1,0]
	v_cvt_pk_bf16_f32 v44, v48, v49
	v_add_co_u32_e32 v48, vcc, s17, v146
	v_cvt_pk_bf16_f32 v45, v50, v51
	v_cvt_pk_bf16_f32 v46, v46, v47
	v_cvt_pk_bf16_f32 v47, v56, v57
	v_addc_co_u32_e32 v49, vcc, 0, v147, vcc
	global_store_dwordx4 v[48:49], v[44:47], off
	v_pk_mul_f32 v[42:43], v[42:43], v[52:53] op_sel_hi:[1,0]
	v_pk_mul_f32 v[40:41], v[40:41], v[52:53] op_sel_hi:[1,0]
	v_pk_mul_f32 v[44:45], v[38:39], v[52:53] op_sel_hi:[1,0]
	v_pk_mul_f32 v[38:39], v[36:37], v[52:53] op_sel_hi:[1,0]
	v_cvt_pk_bf16_f32 v36, v40, v41
	v_cvt_pk_bf16_f32 v37, v42, v43
	v_cvt_pk_bf16_f32 v38, v38, v39
	v_cvt_pk_bf16_f32 v39, v44, v45
	global_store_dwordx4 v[54:55], v[36:39], off offset:256
	s_mov_b32 s17, 0xa0000
	s_nop 0
	v_ffbh_u32_e32 v36, v251
	v_min_u32_e32 v38, 32, v36
	v_lshlrev_b64 v[36:37], v38, v[250:251]
	v_min_u32_e32 v36, 1, v36
	v_or_b32_e32 v36, v37, v36
	v_cvt_f32_u32_e32 v36, v36
	v_sub_u32_e32 v37, 32, v38
	v_lshl_add_u64 v[38:39], v[146:147], 0, s[24:25]
	s_mov_b64 s[24:25], 0xb0000
	v_ldexp_f32 v36, v36, v37
	v_fmamk_f32 v36, v36, 0x2b000000, v217
	v_rsq_f32_e32 v36, v36
	s_nop 0
	v_pk_mul_f32 v[32:33], v[32:33], v[36:37] op_sel_hi:[1,0]
	v_pk_mul_f32 v[34:35], v[34:35], v[36:37] op_sel_hi:[1,0]
	v_pk_mul_f32 v[40:41], v[30:31], v[36:37] op_sel_hi:[1,0]
	v_pk_mul_f32 v[30:31], v[28:29], v[36:37] op_sel_hi:[1,0]
	v_cvt_pk_bf16_f32 v28, v32, v33
	v_add_co_u32_e32 v32, vcc, s17, v146
	v_cvt_pk_bf16_f32 v29, v34, v35
	v_cvt_pk_bf16_f32 v30, v30, v31
	v_cvt_pk_bf16_f32 v31, v40, v41
	v_addc_co_u32_e32 v33, vcc, 0, v147, vcc
	global_store_dwordx4 v[32:33], v[28:31], off
	v_pk_mul_f32 v[26:27], v[26:27], v[36:37] op_sel_hi:[1,0]
	v_pk_mul_f32 v[24:25], v[24:25], v[36:37] op_sel_hi:[1,0]
	v_pk_mul_f32 v[28:29], v[22:23], v[36:37] op_sel_hi:[1,0]
	v_pk_mul_f32 v[22:23], v[20:21], v[36:37] op_sel_hi:[1,0]
	v_cvt_pk_bf16_f32 v20, v24, v25
	v_cvt_pk_bf16_f32 v21, v26, v27
	v_cvt_pk_bf16_f32 v22, v22, v23
	v_cvt_pk_bf16_f32 v23, v28, v29
	global_store_dwordx4 v[38:39], v[20:23], off offset:256
	s_mov_b32 s17, 0xb0000
	s_nop 0
	v_ffbh_u32_e32 v20, v227
	v_min_u32_e32 v22, 32, v20
	v_lshlrev_b64 v[20:21], v22, v[226:227]
	v_min_u32_e32 v20, 1, v20
	v_or_b32_e32 v20, v21, v20
	v_cvt_f32_u32_e32 v20, v20
	v_sub_u32_e32 v21, 32, v22
	v_lshl_add_u64 v[22:23], v[146:147], 0, s[24:25]
	s_mov_b64 s[24:25], -1
	v_ldexp_f32 v20, v20, v21
	v_fmamk_f32 v20, v20, 0x2b000000, v217
	v_rsq_f32_e32 v20, v20
	s_nop 0
	v_pk_mul_f32 v[16:17], v[16:17], v[20:21] op_sel_hi:[1,0]
	v_pk_mul_f32 v[18:19], v[18:19], v[20:21] op_sel_hi:[1,0]
	v_pk_mul_f32 v[24:25], v[14:15], v[20:21] op_sel_hi:[1,0]
	v_pk_mul_f32 v[14:15], v[12:13], v[20:21] op_sel_hi:[1,0]
	v_cvt_pk_bf16_f32 v12, v16, v17
	v_add_co_u32_e32 v16, vcc, s17, v146
	v_cvt_pk_bf16_f32 v13, v18, v19
	v_cvt_pk_bf16_f32 v14, v14, v15
	v_cvt_pk_bf16_f32 v15, v24, v25
	v_addc_co_u32_e32 v17, vcc, 0, v147, vcc
	global_store_dwordx4 v[16:17], v[12:15], off
	v_pk_mul_f32 v[10:11], v[10:11], v[20:21] op_sel_hi:[1,0]
	v_pk_mul_f32 v[8:9], v[8:9], v[20:21] op_sel_hi:[1,0]
	v_pk_mul_f32 v[12:13], v[6:7], v[20:21] op_sel_hi:[1,0]
	v_pk_mul_f32 v[6:7], v[4:5], v[20:21] op_sel_hi:[1,0]
	v_cvt_pk_bf16_f32 v4, v8, v9
	v_cvt_pk_bf16_f32 v5, v10, v11
	v_cvt_pk_bf16_f32 v6, v6, v7
	v_cvt_pk_bf16_f32 v7, v12, v13
	s_andn2_b64 vcc, exec, s[4:5]
	global_store_dwordx4 v[22:23], v[4:7], off offset:256
	s_cbranch_vccnz .LBB0_1195
	s_andn2_b64 vcc, exec, s[8:9]
	s_cbranch_vccnz .LBB0_1194
	s_barrier
	s_branch .LBB0_1194

.LBB0_3455:
	s_ashr_i32 s29, s28, 31
	s_lshl_b64 s[10:11], s[28:29], 20
	s_add_u32 s30, s14, s10
	s_addc_u32 s31, s39, s11
	s_and_b64 s[10:11], s[4:5], exec
	s_cselect_b32 s12, s31, s7
	s_cselect_b32 s13, s30, s6
	s_ashr_i32 s27, s26, 31
	s_lshl_b64 s[10:11], s[26:27], 20
	s_add_u32 s34, s52, s10
	s_addc_u32 s35, s53, s11
	s_and_b64 s[10:11], s[4:5], exec
	s_cselect_b32 s27, s35, s9
	s_cselect_b32 s29, s34, s8
	s_add_u32 s6, s6, 0x80080
	s_addc_u32 s7, s7, 0
	s_add_u32 s36, s8, 0x100
	s_addc_u32 s37, s9, 0
	s_mov_b32 s42, -2
	v_and_b32_e32 v250, 63, v0
	v_lshlrev_b32_e32 v250, 2, v250
	s_lshl_b32 s98, s58, 8
	s_add_i32 s98, s98, s64
	s_lshl_b32 s98, s98, 2
	s_add_u32 s98, s24, s98
	s_addc_u32 s99, s25, 0
	s_lshr_b32 m0, s55, 2
	s_sub_i32 m0, s55, m0
	s_add_i32 m0, m0, 0x20000
	s_nop 0
	global_load_lds_dword v250, s[98:99]
	global_load_lds_dword v250, s[98:99] offset:512
	v_and_b32_e32 v251, 31, v0
	v_bfe_u32 v252, v0, 5, 1
	v_lshl_add_u32 v251, v252, 7, v251
	v_lshlrev_b32_e32 v251, 2, v251
	s_add_i32 s98, s15, 55
	s_lshl_b32 s98, s98, 8
	s_add_i32 s98, s98, s65
	s_lshl_b32 s98, s98, 2
	s_add_u32 s98, s51, s98
	s_addc_u32 s99, s33, 0
	s_add_i32 m0, m0, 0x100
	s_nop 0
	global_load_lds_dword v251, s[98:99]
	s_add_u32 s8, s6, 0xfff80080
	s_addc_u32 s9, s7, -1
	s_add_i32 s43, 0, 0x10000
	s_cmp_eq_u32 s42, 28
	s_cselect_b32 s11, s12, s9
	s_cselect_b32 s10, s13, s8
	v_add_u32_e32 v2, s43, v194
	s_cselect_b32 s9, s27, s37
	s_cselect_b32 s8, s29, s36
	s_add_i32 s48, 0, 0x14000
	ds_read_b128 v[30:33], v2
	ds_read_b128 v[34:37], v2 offset:1024
	ds_read_b128 v[46:49], v2 offset:2048
	ds_read_b128 v[50:53], v2 offset:3072
	v_add_u32_e32 v2, s48, v194
	ds_read_b128 v[162:165], v2
	ds_read_b128 v[166:169], v2 offset:1024
	ds_read_b128 v[170:173], v2 offset:2048
	ds_read_b128 v[174:177], v2 offset:3072
	v_lshl_add_u64 v[4:5], s[6:7], 0, v[158:159]
	s_add_i32 m0, s55, 0xc000
	ds_read_b128 v[178:181], v195
	ds_read_b128 v[182:185], v195 offset:1024
	ds_read_b128 v[186:189], v195 offset:2048
	ds_read_b128 v[196:199], v195 offset:3072
	ds_read_b128 v[204:207], v195 offset:4096
	ds_read_b128 v[208:211], v195 offset:5120
	ds_read_b128 v[212:215], v195 offset:6144
	ds_read_b128 v[226:229], v195 offset:7168
	global_load_lds_dwordx4 v[4:5], off
	v_lshl_add_u64 v[4:5], s[6:7], 0, v[160:161]
	s_add_i32 m0, s55, 0xe000
	s_nop 0
	global_load_lds_dwordx4 v[4:5], off
	s_waitcnt vmcnt(11)
	s_waitcnt lgkmcnt(0)
	s_barrier
	v_mfma_i32_16x16x64_i8 v[146:149], v[30:33], v[178:181], 0
	v_mfma_i32_16x16x64_i8 v[142:145], v[46:49], v[178:181], 0
	v_mfma_i32_16x16x64_i8 v[130:133], v[30:33], v[186:189], 0
	v_mfma_i32_16x16x64_i8 v[126:129], v[46:49], v[186:189], 0
	v_mfma_i32_16x16x64_i8 v[114:117], v[30:33], v[204:207], 0
	v_mfma_i32_16x16x64_i8 v[110:113], v[46:49], v[204:207], 0
	v_mfma_i32_16x16x64_i8 v[98:101], v[30:33], v[212:215], 0
	v_mfma_i32_16x16x64_i8 v[94:97], v[46:49], v[212:215], 0
	v_mfma_i32_16x16x64_i8 v[146:149], v[34:37], v[182:185], v[146:149]
	v_mfma_i32_16x16x64_i8 v[142:145], v[50:53], v[182:185], v[142:145]
	v_mfma_i32_16x16x64_i8 v[130:133], v[34:37], v[196:199], v[130:133]
	v_mfma_i32_16x16x64_i8 v[126:129], v[50:53], v[196:199], v[126:129]
	v_mfma_i32_16x16x64_i8 v[114:117], v[34:37], v[208:211], v[114:117]
	v_mfma_i32_16x16x64_i8 v[110:113], v[50:53], v[208:211], v[110:113]
	v_mfma_i32_16x16x64_i8 v[98:101], v[34:37], v[226:229], v[98:101]
	v_mfma_i32_16x16x64_i8 v[94:97], v[50:53], v[226:229], v[94:97]
	v_mfma_i32_16x16x64_i8 v[138:141], v[162:165], v[178:181], 0
	v_mfma_i32_16x16x64_i8 v[134:137], v[170:173], v[178:181], 0
	v_mfma_i32_16x16x64_i8 v[122:125], v[162:165], v[186:189], 0
	v_mfma_i32_16x16x64_i8 v[118:121], v[170:173], v[186:189], 0
	v_mfma_i32_16x16x64_i8 v[106:109], v[162:165], v[204:207], 0
	v_mfma_i32_16x16x64_i8 v[102:105], v[170:173], v[204:207], 0
	v_mfma_i32_16x16x64_i8 v[90:93], v[162:165], v[212:215], 0
	v_mfma_i32_16x16x64_i8 v[86:89], v[170:173], v[212:215], 0
	v_mfma_i32_16x16x64_i8 v[138:141], v[166:169], v[182:185], v[138:141]
	v_mfma_i32_16x16x64_i8 v[134:137], v[174:177], v[182:185], v[134:137]
	v_mfma_i32_16x16x64_i8 v[122:125], v[166:169], v[196:199], v[122:125]
	v_mfma_i32_16x16x64_i8 v[118:121], v[174:177], v[196:199], v[118:121]
	v_mfma_i32_16x16x64_i8 v[106:109], v[166:169], v[208:211], v[106:109]
	v_mfma_i32_16x16x64_i8 v[102:105], v[174:177], v[208:211], v[102:105]
	v_mfma_i32_16x16x64_i8 v[90:93], v[166:169], v[226:229], v[90:93]
	v_mfma_i32_16x16x64_i8 v[86:89], v[174:177], v[226:229], v[86:89]
	s_barrier
	s_add_i32 s43, s43, s54
	v_lshl_add_u64 v[190:191], s[8:9], 0, v[154:155]
	s_mov_b32 m0, s43
	ds_read_b128 v[178:181], v195 offset:16384
	ds_read_b128 v[182:185], v195 offset:17408
	ds_read_b128 v[186:189], v195 offset:18432
	ds_read_b128 v[196:199], v195 offset:19456
	ds_read_b128 v[204:207], v195 offset:20480
	ds_read_b128 v[208:211], v195 offset:21504
	ds_read_b128 v[212:215], v195 offset:22528
	ds_read_b128 v[226:229], v195 offset:23552
	global_load_lds_dwordx4 v[190:191], off
	s_add_i32 m0, s43, 0x2000
	s_add_u32 s44, s8, 0x80000
	v_lshl_add_u64 v[230:231], s[8:9], 0, v[150:151]
	s_addc_u32 s45, s9, 0
	s_add_i32 s43, s48, s54
	global_load_lds_dwordx4 v[230:231], off
	v_lshl_add_u64 v[4:5], s[44:45], 0, v[154:155]
	s_mov_b32 m0, s43
	v_lshl_add_u64 v[232:233], s[10:11], 0, v[156:157]
	global_load_lds_dwordx4 v[4:5], off
	v_lshl_add_u64 v[4:5], s[44:45], 0, v[150:151]
	s_add_i32 m0, s43, 0x2000
	v_lshl_add_u64 v[234:235], s[10:11], 0, v[152:153]
	global_load_lds_dwordx4 v[4:5], off
	s_mov_b32 m0, s55
	s_nop 0
	global_load_lds_dwordx4 v[232:233], off
	s_mov_b32 m0, s56
	s_nop 0
	global_load_lds_dwordx4 v[234:235], off
	s_waitcnt vmcnt(11)
	s_waitcnt lgkmcnt(0)
	s_barrier
	v_mfma_i32_16x16x64_i8 v[82:85], v[30:33], v[178:181], 0
	v_mfma_i32_16x16x64_i8 v[78:81], v[46:49], v[178:181], 0
	v_mfma_i32_16x16x64_i8 v[66:69], v[30:33], v[186:189], 0
	v_mfma_i32_16x16x64_i8 v[62:65], v[46:49], v[186:189], 0
	v_mfma_i32_16x16x64_i8 v[42:45], v[30:33], v[204:207], 0
	v_mfma_i32_16x16x64_i8 v[38:41], v[46:49], v[204:207], 0
	v_mfma_i32_16x16x64_i8 v[18:21], v[30:33], v[212:215], 0
	v_mfma_i32_16x16x64_i8 v[14:17], v[46:49], v[212:215], 0
	v_mfma_i32_16x16x64_i8 v[82:85], v[34:37], v[182:185], v[82:85]
	v_mfma_i32_16x16x64_i8 v[78:81], v[50:53], v[182:185], v[78:81]
	v_mfma_i32_16x16x64_i8 v[66:69], v[34:37], v[196:199], v[66:69]
	v_mfma_i32_16x16x64_i8 v[62:65], v[50:53], v[196:199], v[62:65]
	v_mfma_i32_16x16x64_i8 v[42:45], v[34:37], v[208:211], v[42:45]
	v_mfma_i32_16x16x64_i8 v[38:41], v[50:53], v[208:211], v[38:41]
	v_mfma_i32_16x16x64_i8 v[18:21], v[34:37], v[226:229], v[18:21]
	v_mfma_i32_16x16x64_i8 v[14:17], v[50:53], v[226:229], v[14:17]
	v_mfma_i32_16x16x64_i8 v[26:29], v[162:165], v[204:207], 0
	v_mfma_i32_16x16x64_i8 v[22:25], v[170:173], v[204:207], 0
	v_mfma_i32_16x16x64_i8 v[10:13], v[162:165], v[212:215], 0
	v_mfma_i32_16x16x64_i8 v[4:7], v[170:173], v[212:215], 0
	v_mfma_i32_16x16x64_i8 v[30:33], v[162:165], v[178:181], 0
	v_mfma_i32_16x16x64_i8 v[34:37], v[170:173], v[178:181], 0
	v_mfma_i32_16x16x64_i8 v[46:49], v[162:165], v[186:189], 0
	v_mfma_i32_16x16x64_i8 v[50:53], v[170:173], v[186:189], 0
	v_mfma_i32_16x16x64_i8 v[26:29], v[166:169], v[208:211], v[26:29]
	v_mfma_i32_16x16x64_i8 v[22:25], v[174:177], v[208:211], v[22:25]
	v_mfma_i32_16x16x64_i8 v[10:13], v[166:169], v[226:229], v[10:13]
	v_mfma_i32_16x16x64_i8 v[4:7], v[174:177], v[226:229], v[4:7]
	v_mfma_i32_16x16x64_i8 v[30:33], v[166:169], v[182:185], v[30:33]
	v_mfma_i32_16x16x64_i8 v[34:37], v[174:177], v[182:185], v[34:37]
	v_mfma_i32_16x16x64_i8 v[46:49], v[166:169], v[196:199], v[46:49]
	v_mfma_i32_16x16x64_i8 v[50:53], v[174:177], v[196:199], v[50:53]
	s_barrier
	s_add_i32 s43, 0, 0x18000
	v_add_u32_e32 v2, s43, v194
	s_add_i32 s44, 0, 0x1c000
	ds_read_b128 v[54:57], v2
	ds_read_b128 v[58:61], v2 offset:1024
	ds_read_b128 v[70:73], v2 offset:2048
	ds_read_b128 v[74:77], v2 offset:3072
	v_add_u32_e32 v2, s44, v194
	ds_read_b128 v[162:165], v2
	ds_read_b128 v[166:169], v2 offset:1024
	ds_read_b128 v[170:173], v2 offset:2048
	ds_read_b128 v[174:177], v2 offset:3072
	s_add_u32 s10, s10, 0x80000
	s_addc_u32 s11, s11, 0
	s_mov_b32 m0, s57
	v_lshl_add_u64 v[8:9], s[10:11], 0, v[156:157]
	ds_read_b128 v[178:181], v195 offset:32768
	ds_read_b128 v[182:185], v195 offset:33792
	ds_read_b128 v[186:189], v195 offset:34816
	ds_read_b128 v[196:199], v195 offset:35840
	ds_read_b128 v[204:207], v195 offset:36864
	ds_read_b128 v[208:211], v195 offset:37888
	ds_read_b128 v[212:215], v195 offset:38912
	ds_read_b128 v[226:229], v195 offset:39936
	global_load_lds_dwordx4 v[8:9], off
	v_lshl_add_u64 v[8:9], s[10:11], 0, v[152:153]
	s_mov_b32 m0, s59
	s_nop 0
	global_load_lds_dwordx4 v[8:9], off
	s_waitcnt vmcnt(8)
	s_waitcnt lgkmcnt(0)
	s_barrier
	v_mfma_i32_16x16x64_i8 v[146:149], v[54:57], v[178:181], v[146:149]
	v_mfma_i32_16x16x64_i8 v[142:145], v[70:73], v[178:181], v[142:145]
	v_mfma_i32_16x16x64_i8 v[130:133], v[54:57], v[186:189], v[130:133]
	v_mfma_i32_16x16x64_i8 v[126:129], v[70:73], v[186:189], v[126:129]
	v_mfma_i32_16x16x64_i8 v[114:117], v[54:57], v[204:207], v[114:117]
	v_mfma_i32_16x16x64_i8 v[110:113], v[70:73], v[204:207], v[110:113]
	v_mfma_i32_16x16x64_i8 v[98:101], v[54:57], v[212:215], v[98:101]
	v_mfma_i32_16x16x64_i8 v[94:97], v[70:73], v[212:215], v[94:97]
	v_mfma_i32_16x16x64_i8 v[146:149], v[58:61], v[182:185], v[146:149]
	v_mfma_i32_16x16x64_i8 v[142:145], v[74:77], v[182:185], v[142:145]
	v_mfma_i32_16x16x64_i8 v[130:133], v[58:61], v[196:199], v[130:133]
	v_mfma_i32_16x16x64_i8 v[126:129], v[74:77], v[196:199], v[126:129]
	v_mfma_i32_16x16x64_i8 v[114:117], v[58:61], v[208:211], v[114:117]
	v_mfma_i32_16x16x64_i8 v[110:113], v[74:77], v[208:211], v[110:113]
	v_mfma_i32_16x16x64_i8 v[98:101], v[58:61], v[226:229], v[98:101]
	v_mfma_i32_16x16x64_i8 v[94:97], v[74:77], v[226:229], v[94:97]
	v_mfma_i32_16x16x64_i8 v[138:141], v[162:165], v[178:181], v[138:141]
	v_mfma_i32_16x16x64_i8 v[134:137], v[170:173], v[178:181], v[134:137]
	v_mfma_i32_16x16x64_i8 v[122:125], v[162:165], v[186:189], v[122:125]
	v_mfma_i32_16x16x64_i8 v[118:121], v[170:173], v[186:189], v[118:121]
	v_mfma_i32_16x16x64_i8 v[106:109], v[162:165], v[204:207], v[106:109]
	v_mfma_i32_16x16x64_i8 v[102:105], v[170:173], v[204:207], v[102:105]
	v_mfma_i32_16x16x64_i8 v[90:93], v[162:165], v[212:215], v[90:93]
	v_mfma_i32_16x16x64_i8 v[86:89], v[170:173], v[212:215], v[86:89]
	v_mfma_i32_16x16x64_i8 v[138:141], v[166:169], v[182:185], v[138:141]
	v_mfma_i32_16x16x64_i8 v[134:137], v[174:177], v[182:185], v[134:137]
	v_mfma_i32_16x16x64_i8 v[122:125], v[166:169], v[196:199], v[122:125]
	v_mfma_i32_16x16x64_i8 v[118:121], v[174:177], v[196:199], v[118:121]
	v_mfma_i32_16x16x64_i8 v[106:109], v[166:169], v[208:211], v[106:109]
	v_mfma_i32_16x16x64_i8 v[102:105], v[174:177], v[208:211], v[102:105]
	v_mfma_i32_16x16x64_i8 v[90:93], v[166:169], v[226:229], v[90:93]
	v_mfma_i32_16x16x64_i8 v[86:89], v[174:177], v[226:229], v[86:89]
	s_barrier
	s_add_i32 s10, s43, s54
	v_lshl_add_u64 v[8:9], v[190:191], 0, s[94:95]
	s_mov_b32 m0, s10
	ds_read_b128 v[178:181], v195 offset:49152
	ds_read_b128 v[182:185], v195 offset:50176
	ds_read_b128 v[186:189], v195 offset:51200
	ds_read_b128 v[196:199], v195 offset:52224
	ds_read_b128 v[204:207], v195 offset:53248
	ds_read_b128 v[208:211], v195 offset:54272
	ds_read_b128 v[212:215], v195 offset:55296
	ds_read_b128 v[226:229], v195 offset:56320
	global_load_lds_dwordx4 v[8:9], off
	s_add_i32 m0, s10, 0x2000
	s_add_u32 s8, s8, 0x80080
	v_lshl_add_u64 v[8:9], v[230:231], 0, s[94:95]
	s_addc_u32 s9, s9, 0
	s_add_i32 s10, s44, s54
	global_load_lds_dwordx4 v[8:9], off
	v_lshl_add_u64 v[8:9], s[8:9], 0, v[154:155]
	s_mov_b32 m0, s10
	s_nop 0
	global_load_lds_dwordx4 v[8:9], off
	v_lshl_add_u64 v[8:9], s[8:9], 0, v[150:151]
	s_add_i32 m0, s10, 0x2000
	s_nop 0
	global_load_lds_dwordx4 v[8:9], off
	v_lshl_add_u64 v[8:9], v[232:233], 0, s[94:95]
	s_mov_b32 m0, s71
	s_nop 0
	global_load_lds_dwordx4 v[8:9], off
	v_lshl_add_u64 v[8:9], v[234:235], 0, s[94:95]
	s_mov_b32 m0, s74
	s_nop 0
	global_load_lds_dwordx4 v[8:9], off
	s_waitcnt vmcnt(8)
	s_waitcnt lgkmcnt(0)
	s_barrier
	v_mfma_i32_16x16x64_i8 v[82:85], v[54:57], v[178:181], v[82:85]
	v_mfma_i32_16x16x64_i8 v[78:81], v[70:73], v[178:181], v[78:81]
	v_mfma_i32_16x16x64_i8 v[66:69], v[54:57], v[186:189], v[66:69]
	v_mfma_i32_16x16x64_i8 v[62:65], v[70:73], v[186:189], v[62:65]
	v_mfma_i32_16x16x64_i8 v[42:45], v[54:57], v[204:207], v[42:45]
	v_mfma_i32_16x16x64_i8 v[38:41], v[70:73], v[204:207], v[38:41]
	v_mfma_i32_16x16x64_i8 v[18:21], v[54:57], v[212:215], v[18:21]
	v_mfma_i32_16x16x64_i8 v[14:17], v[70:73], v[212:215], v[14:17]
	v_mfma_i32_16x16x64_i8 v[82:85], v[58:61], v[182:185], v[82:85]
	v_mfma_i32_16x16x64_i8 v[78:81], v[74:77], v[182:185], v[78:81]
	v_mfma_i32_16x16x64_i8 v[66:69], v[58:61], v[196:199], v[66:69]
	v_mfma_i32_16x16x64_i8 v[62:65], v[74:77], v[196:199], v[62:65]
	v_mfma_i32_16x16x64_i8 v[42:45], v[58:61], v[208:211], v[42:45]
	v_mfma_i32_16x16x64_i8 v[38:41], v[74:77], v[208:211], v[38:41]
	v_mfma_i32_16x16x64_i8 v[18:21], v[58:61], v[226:229], v[18:21]
	v_mfma_i32_16x16x64_i8 v[14:17], v[74:77], v[226:229], v[14:17]
	v_mfma_i32_16x16x64_i8 v[30:33], v[162:165], v[178:181], v[30:33]
	v_mfma_i32_16x16x64_i8 v[74:77], v[166:169], v[182:185], v[30:33]
	v_mfma_i32_16x16x64_i8 v[30:33], v[170:173], v[178:181], v[34:37]
	v_mfma_i32_16x16x64_i8 v[70:73], v[174:177], v[182:185], v[30:33]
	v_mfma_i32_16x16x64_i8 v[30:33], v[162:165], v[186:189], v[46:49]
	v_mfma_i32_16x16x64_i8 v[58:61], v[166:169], v[196:199], v[30:33]
	v_mfma_i32_16x16x64_i8 v[30:33], v[170:173], v[186:189], v[50:53]
	v_mfma_i32_16x16x64_i8 v[26:29], v[162:165], v[204:207], v[26:29]
	v_mfma_i32_16x16x64_i8 v[22:25], v[170:173], v[204:207], v[22:25]
	v_mfma_i32_16x16x64_i8 v[8:11], v[162:165], v[212:215], v[10:13]
	v_mfma_i32_16x16x64_i8 v[4:7], v[170:173], v[212:215], v[4:7]
	v_mfma_i32_16x16x64_i8 v[54:57], v[174:177], v[196:199], v[30:33]
	v_mfma_i32_16x16x64_i8 v[26:29], v[166:169], v[208:211], v[26:29]
	v_mfma_i32_16x16x64_i8 v[22:25], v[174:177], v[208:211], v[22:25]
	v_mfma_i32_16x16x64_i8 v[10:13], v[166:169], v[226:229], v[8:11]
	v_mfma_i32_16x16x64_i8 v[6:9], v[174:177], v[226:229], v[4:7]
	s_barrier
	s_add_i32 s42, s42, 2
	s_add_u32 s6, s6, 0x100
	s_addc_u32 s7, s7, 0
	s_add_u32 s36, s36, 0x100
	s_addc_u32 s37, s37, 0
	s_cmp_gt_u32 s42, 29
